# LDS-DMA attention loop: one DMA issue per MFMA gap across the first eight MFMAs of the tile
# speedup vs baseline: 1.0269x; 1.0015x over previous
.Lattn_nf_loop:
	ds_read_b128 v[98:101], v82 offset:0
	ds_read_b128 v[102:105], v83 offset:0
	ds_read_b128 v[106:109], v84 offset:0
	ds_read_b128 v[110:113], v85 offset:0
	s_and_b32 s10, s15, 1
	s_xor_b32 s10, s10, 1
	s_lshl_b32 s10, s10, 15
	s_add_i32 s10, s10, s11
	s_add_i32 s6, s10, 0x10000
	s_waitcnt lgkmcnt(3)
	v_mfma_f32_32x32x16_bf16 v[138:153], v[98:101], v[10:13], 0
	ds_read_b128 v[98:101], v82 offset:8192
	s_add_i32 m0, s10, 0x0
	s_nop 0
	global_load_lds_dwordx4 v124, s[64:65]
	s_waitcnt lgkmcnt(3)
	v_mfma_f32_32x32x16_bf16 v[138:153], v[102:105], v[14:17], v[138:153]
	ds_read_b128 v[102:105], v83 offset:8192
	s_add_i32 m0, s10, 0x2000
	s_nop 0
	global_load_lds_dwordx4 v124, s[66:67]
	s_waitcnt lgkmcnt(3)
	v_mfma_f32_32x32x16_bf16 v[138:153], v[106:109], v[2:5], v[138:153]
	ds_read_b128 v[106:109], v84 offset:8192
	s_add_i32 m0, s10, 0x4000
	s_nop 0
	global_load_lds_dwordx4 v124, s[68:69]
	s_waitcnt lgkmcnt(3)
	v_mfma_f32_32x32x16_bf16 v[138:153], v[110:113], v[6:9], v[138:153]
	ds_read_b128 v[110:113], v85 offset:8192
	s_add_i32 m0, s10, 0x6000
	s_nop 0
	global_load_lds_dwordx4 v124, s[70:71]
	v_add_u32_e32 v124, s36, v124
	s_waitcnt lgkmcnt(3)
	v_mfma_f32_32x32x16_bf16 v[154:169], v[98:101], v[10:13], 0
	ds_read_b128 v[98:101], v82 offset:16384
	s_add_i32 m0, s6, 0x0
	s_nop 0
	global_load_lds_dwordx4 v125, s[72:73]
	ds_read_b128 v[128:131], v86 offset:0
	ds_read_b128 v[184:187], v86 offset:8192
	v_exp_f32_e32 v138, v138
	v_exp_f32_e32 v139, v139
	v_exp_f32_e32 v140, v140
	v_exp_f32_e32 v141, v141
	v_exp_f32_e32 v142, v142
	v_exp_f32_e32 v143, v143
	s_waitcnt lgkmcnt(5)
	v_mfma_f32_32x32x16_bf16 v[154:169], v[102:105], v[14:17], v[154:169]
	ds_read_b128 v[102:105], v83 offset:16384
	s_add_i32 m0, s6, 0x2000
	s_nop 0
	global_load_lds_dwordx4 v125, s[74:75]
	ds_read_b128 v[188:191], v86 offset:16384
	ds_read_b128 v[192:195], v86 offset:24576
	v_exp_f32_e32 v144, v144
	v_exp_f32_e32 v145, v145
	v_add_f32_e32 v122, v138, v122
	v_add_f32_e32 v122, v139, v122
	v_add_f32_e32 v122, v140, v122
	v_add_f32_e32 v122, v141, v122
	v_add_f32_e32 v122, v142, v122
	v_add_f32_e32 v122, v143, v122
	v_add_f32_e32 v122, v144, v122
	v_add_f32_e32 v122, v145, v122
	v_cvt_pk_bf16_f32 v114, v138, v139
	v_cvt_pk_bf16_f32 v115, v140, v141
	v_cvt_pk_bf16_f32 v116, v142, v143
	v_cvt_pk_bf16_f32 v117, v144, v145
	s_waitcnt lgkmcnt(7)
	v_mfma_f32_32x32x16_bf16 v[154:169], v[106:109], v[2:5], v[154:169]
	ds_read_b128 v[106:109], v84 offset:16384
	s_add_i32 m0, s6, 0x4000
	s_nop 0
	global_load_lds_dwordx4 v125, s[76:77]
	ds_read_b128 v[196:199], v87 offset:0
	v_exp_f32_e32 v146, v146
	v_exp_f32_e32 v147, v147
	s_waitcnt lgkmcnt(8)
	v_mfma_f32_32x32x16_bf16 v[154:169], v[110:113], v[6:9], v[154:169]
	ds_read_b128 v[110:113], v85 offset:16384
	s_add_i32 m0, s6, 0x6000
	s_nop 0
	global_load_lds_dwordx4 v125, s[78:79]
	v_add_u32_e32 v125, s38, v125
	ds_read_b128 v[216:219], v87 offset:8192
	v_exp_f32_e32 v148, v148
	v_exp_f32_e32 v149, v149
	s_waitcnt lgkmcnt(8)
	v_mfma_f32_32x32x16_bf16 v[18:33], v[128:131], v[114:117], v[18:33]
	v_exp_f32_e32 v150, v150
	v_exp_f32_e32 v151, v151
	s_waitcnt lgkmcnt(7)
	v_mfma_f32_32x32x16_bf16 v[34:49], v[184:187], v[114:117], v[34:49]
	ds_read_b128 v[200:203], v87 offset:16384
	v_exp_f32_e32 v152, v152
	v_exp_f32_e32 v153, v153
	s_waitcnt lgkmcnt(6)
	v_mfma_f32_32x32x16_bf16 v[50:65], v[188:191], v[114:117], v[50:65]
	ds_read_b128 v[204:207], v87 offset:24576
	v_add_f32_e32 v122, v146, v122
	v_add_f32_e32 v122, v147, v122
	v_add_f32_e32 v122, v148, v122
	v_add_f32_e32 v122, v149, v122
	s_waitcnt lgkmcnt(6)
	v_mfma_f32_32x32x16_bf16 v[66:81], v[192:195], v[114:117], v[66:81]
	v_add_f32_e32 v122, v150, v122
	v_add_f32_e32 v122, v151, v122
	v_add_f32_e32 v122, v152, v122
	v_add_f32_e32 v122, v153, v122
	v_cvt_pk_bf16_f32 v118, v146, v147
	v_cvt_pk_bf16_f32 v119, v148, v149
	v_cvt_pk_bf16_f32 v120, v150, v151
	v_cvt_pk_bf16_f32 v121, v152, v153
	v_mfma_f32_32x32x16_bf16 v[138:153], v[98:101], v[10:13], 0
	ds_read_b128 v[98:101], v82 offset:24576
	ds_read_b128 v[128:131], v88 offset:0
	v_exp_f32_e32 v154, v154
	v_exp_f32_e32 v155, v155
	v_mfma_f32_32x32x16_bf16 v[138:153], v[102:105], v[14:17], v[138:153]
	ds_read_b128 v[102:105], v83 offset:24576
	ds_read_b128 v[184:187], v88 offset:8192
	v_exp_f32_e32 v156, v156
	v_exp_f32_e32 v157, v157
	s_waitcnt lgkmcnt(8)
	v_mfma_f32_32x32x16_bf16 v[18:33], v[196:199], v[118:121], v[18:33]
	v_exp_f32_e32 v158, v158
	v_exp_f32_e32 v159, v159
	s_waitcnt lgkmcnt(6)
	v_mfma_f32_32x32x16_bf16 v[34:49], v[216:219], v[118:121], v[34:49]
	ds_read_b128 v[188:191], v88 offset:16384
	v_exp_f32_e32 v160, v160
	v_exp_f32_e32 v161, v161
	s_waitcnt lgkmcnt(6)
	v_mfma_f32_32x32x16_bf16 v[50:65], v[200:203], v[118:121], v[50:65]
	ds_read_b128 v[192:195], v88 offset:24576
	v_add_f32_e32 v122, v154, v122
	v_add_f32_e32 v122, v155, v122
	v_add_f32_e32 v122, v156, v122
	v_add_f32_e32 v122, v157, v122
	s_waitcnt lgkmcnt(6)
	v_mfma_f32_32x32x16_bf16 v[66:81], v[204:207], v[118:121], v[66:81]
	v_add_f32_e32 v122, v158, v122
	v_add_f32_e32 v122, v159, v122
	v_add_f32_e32 v122, v160, v122
	v_add_f32_e32 v122, v161, v122
	v_cvt_pk_bf16_f32 v114, v154, v155
	v_cvt_pk_bf16_f32 v115, v156, v157
	v_cvt_pk_bf16_f32 v116, v158, v159
	v_cvt_pk_bf16_f32 v117, v160, v161
	v_mfma_f32_32x32x16_bf16 v[138:153], v[106:109], v[2:5], v[138:153]
	ds_read_b128 v[106:109], v84 offset:24576
	ds_read_b128 v[196:199], v89 offset:0
	v_exp_f32_e32 v162, v162
	v_exp_f32_e32 v163, v163
	v_mfma_f32_32x32x16_bf16 v[138:153], v[110:113], v[6:9], v[138:153]
	ds_read_b128 v[110:113], v85 offset:24576
	ds_read_b128 v[216:219], v89 offset:8192
	v_exp_f32_e32 v164, v164
	v_exp_f32_e32 v165, v165
	s_waitcnt lgkmcnt(8)
	v_mfma_f32_32x32x16_bf16 v[18:33], v[128:131], v[114:117], v[18:33]
	v_exp_f32_e32 v166, v166
	v_exp_f32_e32 v167, v167
	s_waitcnt lgkmcnt(6)
	v_mfma_f32_32x32x16_bf16 v[34:49], v[184:187], v[114:117], v[34:49]
	ds_read_b128 v[200:203], v89 offset:16384
	v_exp_f32_e32 v168, v168
	v_exp_f32_e32 v169, v169
	s_waitcnt lgkmcnt(6)
	v_mfma_f32_32x32x16_bf16 v[50:65], v[188:191], v[114:117], v[50:65]
	ds_read_b128 v[204:207], v89 offset:24576
	v_add_f32_e32 v122, v162, v122
	v_add_f32_e32 v122, v163, v122
	v_add_f32_e32 v122, v164, v122
	v_add_f32_e32 v122, v165, v122
	s_waitcnt lgkmcnt(6)
	v_mfma_f32_32x32x16_bf16 v[66:81], v[192:195], v[114:117], v[66:81]
	v_add_f32_e32 v122, v166, v122
	v_add_f32_e32 v122, v167, v122
	v_add_f32_e32 v122, v168, v122
	v_add_f32_e32 v122, v169, v122
	v_cvt_pk_bf16_f32 v118, v162, v163
	v_cvt_pk_bf16_f32 v119, v164, v165
	v_cvt_pk_bf16_f32 v120, v166, v167
	v_cvt_pk_bf16_f32 v121, v168, v169
	v_mfma_f32_32x32x16_bf16 v[154:169], v[98:101], v[10:13], 0
	ds_read_b128 v[128:131], v90 offset:0
	v_exp_f32_e32 v138, v138
	v_exp_f32_e32 v139, v139
	v_mfma_f32_32x32x16_bf16 v[154:169], v[102:105], v[14:17], v[154:169]
	ds_read_b128 v[184:187], v90 offset:8192
	v_exp_f32_e32 v140, v140
	v_exp_f32_e32 v141, v141
	s_waitcnt lgkmcnt(6)
	v_mfma_f32_32x32x16_bf16 v[18:33], v[196:199], v[118:121], v[18:33]
	v_exp_f32_e32 v142, v142
	v_exp_f32_e32 v143, v143
	s_waitcnt lgkmcnt(4)
	v_mfma_f32_32x32x16_bf16 v[34:49], v[216:219], v[118:121], v[34:49]
	ds_read_b128 v[188:191], v90 offset:16384
	v_exp_f32_e32 v144, v144
	v_exp_f32_e32 v145, v145
	s_waitcnt lgkmcnt(4)
	v_mfma_f32_32x32x16_bf16 v[50:65], v[200:203], v[118:121], v[50:65]
	ds_read_b128 v[192:195], v90 offset:24576
	v_add_f32_e32 v122, v138, v122
	v_add_f32_e32 v122, v139, v122
	v_add_f32_e32 v122, v140, v122
	v_add_f32_e32 v122, v141, v122
	s_waitcnt lgkmcnt(4)
	v_mfma_f32_32x32x16_bf16 v[66:81], v[204:207], v[118:121], v[66:81]
	v_add_f32_e32 v122, v142, v122
	v_add_f32_e32 v122, v143, v122
	v_add_f32_e32 v122, v144, v122
	v_add_f32_e32 v122, v145, v122
	v_cvt_pk_bf16_f32 v114, v138, v139
	v_cvt_pk_bf16_f32 v115, v140, v141
	v_cvt_pk_bf16_f32 v116, v142, v143
	v_cvt_pk_bf16_f32 v117, v144, v145
	v_mfma_f32_32x32x16_bf16 v[154:169], v[106:109], v[2:5], v[154:169]
	ds_read_b128 v[196:199], v91 offset:0
	v_exp_f32_e32 v146, v146
	v_exp_f32_e32 v147, v147
	v_mfma_f32_32x32x16_bf16 v[154:169], v[110:113], v[6:9], v[154:169]
	ds_read_b128 v[216:219], v91 offset:8192
	v_exp_f32_e32 v148, v148
	v_exp_f32_e32 v149, v149
	s_waitcnt lgkmcnt(5)
	v_mfma_f32_32x32x16_bf16 v[18:33], v[128:131], v[114:117], v[18:33]
	v_exp_f32_e32 v150, v150
	v_exp_f32_e32 v151, v151
	s_waitcnt lgkmcnt(4)
	v_mfma_f32_32x32x16_bf16 v[34:49], v[184:187], v[114:117], v[34:49]
	ds_read_b128 v[200:203], v91 offset:16384
	v_exp_f32_e32 v152, v152
	v_exp_f32_e32 v153, v153
	s_waitcnt lgkmcnt(4)
	v_mfma_f32_32x32x16_bf16 v[50:65], v[188:191], v[114:117], v[50:65]
	ds_read_b128 v[204:207], v91 offset:24576
	v_add_f32_e32 v122, v146, v122
	v_add_f32_e32 v122, v147, v122
	v_add_f32_e32 v122, v148, v122
	v_add_f32_e32 v122, v149, v122
	s_waitcnt lgkmcnt(4)
	v_mfma_f32_32x32x16_bf16 v[66:81], v[192:195], v[114:117], v[66:81]
	v_add_f32_e32 v122, v150, v122
	v_add_f32_e32 v122, v151, v122
	v_add_f32_e32 v122, v152, v122
	v_add_f32_e32 v122, v153, v122
	v_cvt_pk_bf16_f32 v118, v146, v147
	v_cvt_pk_bf16_f32 v119, v148, v149
	v_cvt_pk_bf16_f32 v120, v150, v151
	v_cvt_pk_bf16_f32 v121, v152, v153
	s_waitcnt lgkmcnt(3)
	s_nop 0
	v_mfma_f32_32x32x16_bf16 v[18:33], v[196:199], v[118:121], v[18:33]
	ds_read_b128 v[128:131], v92 offset:0
	v_exp_f32_e32 v154, v154
	v_exp_f32_e32 v155, v155
	v_exp_f32_e32 v156, v156
	s_waitcnt lgkmcnt(3)
	v_mfma_f32_32x32x16_bf16 v[34:49], v[216:219], v[118:121], v[34:49]
	ds_read_b128 v[184:187], v92 offset:8192
	v_exp_f32_e32 v157, v157
	v_exp_f32_e32 v158, v158
	v_exp_f32_e32 v159, v159
	v_exp_f32_e32 v160, v160
	s_waitcnt lgkmcnt(3)
	v_mfma_f32_32x32x16_bf16 v[50:65], v[200:203], v[118:121], v[50:65]
	ds_read_b128 v[188:191], v92 offset:16384
	v_exp_f32_e32 v161, v161
	v_add_f32_e32 v122, v154, v122
	v_add_f32_e32 v122, v155, v122
	v_add_f32_e32 v122, v156, v122
	v_add_f32_e32 v122, v157, v122
	v_add_f32_e32 v122, v158, v122
	s_waitcnt lgkmcnt(3)
	v_mfma_f32_32x32x16_bf16 v[66:81], v[204:207], v[118:121], v[66:81]
	ds_read_b128 v[192:195], v92 offset:24576
	v_add_f32_e32 v122, v159, v122
	v_add_f32_e32 v122, v160, v122
	v_add_f32_e32 v122, v161, v122
	v_xor_b32_e32 v82, 0x8000, v82
	v_xor_b32_e32 v83, 0x8000, v83
	v_xor_b32_e32 v84, 0x8000, v84
	v_xor_b32_e32 v85, 0x8000, v85
	v_cvt_pk_bf16_f32 v114, v154, v155
	v_cvt_pk_bf16_f32 v115, v156, v157
	v_cvt_pk_bf16_f32 v116, v158, v159
	v_cvt_pk_bf16_f32 v117, v160, v161
	s_waitcnt lgkmcnt(3)
	s_nop 0
	v_mfma_f32_32x32x16_bf16 v[18:33], v[128:131], v[114:117], v[18:33]
	ds_read_b128 v[196:199], v93 offset:0
	v_exp_f32_e32 v162, v162
	v_exp_f32_e32 v163, v163
	v_exp_f32_e32 v164, v164
	s_waitcnt lgkmcnt(3)
	v_mfma_f32_32x32x16_bf16 v[34:49], v[184:187], v[114:117], v[34:49]
	ds_read_b128 v[216:219], v93 offset:8192
	v_exp_f32_e32 v165, v165
	v_exp_f32_e32 v166, v166
	v_exp_f32_e32 v167, v167
	s_waitcnt lgkmcnt(3)
	v_mfma_f32_32x32x16_bf16 v[50:65], v[188:191], v[114:117], v[50:65]
	ds_read_b128 v[200:203], v93 offset:16384
	v_exp_f32_e32 v168, v168
	v_exp_f32_e32 v169, v169
	v_add_f32_e32 v122, v162, v122
	v_add_f32_e32 v122, v163, v122
	s_waitcnt lgkmcnt(3)
	v_mfma_f32_32x32x16_bf16 v[66:81], v[192:195], v[114:117], v[66:81]
	ds_read_b128 v[204:207], v93 offset:24576
	v_add_f32_e32 v122, v164, v122
	v_add_f32_e32 v122, v165, v122
	v_add_f32_e32 v122, v166, v122
	v_add_f32_e32 v122, v167, v122
	v_add_f32_e32 v122, v168, v122
	v_add_f32_e32 v122, v169, v122
	v_cvt_pk_bf16_f32 v118, v162, v163
	v_cvt_pk_bf16_f32 v119, v164, v165
	v_cvt_pk_bf16_f32 v120, v166, v167
	v_cvt_pk_bf16_f32 v121, v168, v169
	s_waitcnt lgkmcnt(3)
	s_nop 0
	v_mfma_f32_32x32x16_bf16 v[18:33], v[196:199], v[118:121], v[18:33]
	v_xor_b32_e32 v86, 0x8000, v86
	v_xor_b32_e32 v87, 0x8000, v87
	s_waitcnt lgkmcnt(2)
	v_mfma_f32_32x32x16_bf16 v[34:49], v[216:219], v[118:121], v[34:49]
	v_xor_b32_e32 v88, 0x8000, v88
	v_xor_b32_e32 v89, 0x8000, v89
	s_waitcnt lgkmcnt(1)
	v_mfma_f32_32x32x16_bf16 v[50:65], v[200:203], v[118:121], v[50:65]
	v_xor_b32_e32 v90, 0x8000, v90
	v_xor_b32_e32 v91, 0x8000, v91
	s_waitcnt lgkmcnt(0)
	v_mfma_f32_32x32x16_bf16 v[66:81], v[204:207], v[118:121], v[66:81]
	v_xor_b32_e32 v92, 0x8000, v92
	v_xor_b32_e32 v93, 0x8000, v93
	s_waitcnt vmcnt(0)
	s_waitcnt lgkmcnt(0)
	s_barrier
	s_add_i32 s15, s15, 1
	s_cmp_eq_u32 s15, 34
	s_cbranch_scc0 .Lattn_nf_loop
	v_readlane_b32 s64, v175, 0
	v_readlane_b32 s65, v175, 1
	v_readlane_b32 s66, v175, 2
	v_readlane_b32 s67, v175, 3
	v_readlane_b32 s68, v175, 4
	v_readlane_b32 s69, v175, 5
	v_readlane_b32 s70, v175, 6
	v_readlane_b32 s71, v175, 7
	v_readlane_b32 s72, v175, 8
	v_readlane_b32 s73, v175, 9
	v_readlane_b32 s74, v175, 10
	v_readlane_b32 s75, v175, 11
	v_readlane_b32 s76, v175, 12
	v_readlane_b32 s77, v175, 13
	v_readlane_b32 s78, v175, 14
	v_readlane_b32 s79, v175, 15
	s_nop 4
	s_mov_b32 s10, 0x3fb8aa3b
	s_mov_b32 s11, 0xc2ce8ed0
	s_mov_b32 s6, 0x42b17218
	v_cmp_eq_u32_e64 s[40:41], 0, v179
	s_lshl_b32 s30, s14, 1
	v_lshlrev_b32_e32 v196, 3, v178
	v_mov_b32_e32 v197, 0
	v_lshlrev_b32_e32 v198, 4, v179
	v_or3_b32 v198, v198, v177, v180
	v_ashrrev_i32_e32 v199, 31, v198
	v_lshlrev_b64 v[198:199], 11, v[198:199]
	s_mov_b64 s[100:101], 0x18a10000
	v_lshl_add_u64 v[198:199], s[42:43], 0, v[198:199]
	v_lshl_add_u64 v[198:199], v[198:199], 0, s[30:31]
	v_lshl_add_u64 v[198:199], v[198:199], 0, v[196:197]
	v_lshl_add_u64 v[198:199], v[198:199], 0, s[100:101]
	global_load_dwordx2 v[146:147], v[198:199], off
	global_load_dwordx2 v[148:149], v[198:199], off offset:32
	global_load_dwordx2 v[150:151], v[198:199], off offset:64
	global_load_dwordx2 v[152:153], v[198:199], off offset:96
	global_load_dwordx2 v[188:189], v[198:199], off offset:128
	global_load_dwordx2 v[190:191], v[198:199], off offset:160
	global_load_dwordx2 v[192:193], v[198:199], off offset:192
	global_load_dwordx2 v[194:195], v[198:199], off offset:224
	s_mov_b64 s[100:101], exec
	s_and_b64 exec, exec, s[4:5]
	s_cbranch_execz .Lpop_skip
	v_readlane_b32 s14, v255, 22
	v_readlane_b32 s15, v255, 23
	v_mov_b32_e32 v224, 1
	s_nop 4
	global_atomic_add v224, v0, v224, s[14:15] sc0
